# phase 1 projection GEMM: hand-written epilogue for the plain n-tiles (0..13): bf16 via v_cvt_pk_bf16_f32, 16-row groups through a wave-private swizzled LDS image, 128-byte row pieces
# speedup vs baseline: 1.2144x; 1.0013x over previous
; DEVI unsigned pack2(float a, float b) { return (unsigned)f2bf(a) | ((unsigned)f2bf(b) << 16); }
; DEVI void phase1(const Params& p, unsigned char* smem) {
;     ...
; #pragma unroll
;       for (int mi = 0; mi < 4; ++mi) {
;         const int m = m0 + wm * 64 + 16 * mi + col;
;         const int b = m >> 11, t = m & 2047;
; #pragma unroll
;         for (int ni = 0; ni < 4; ++ni) {
;           const int nt = n0 + wn * 64 + 16 * ni;
;           const int n = nt + 4 * quad;
;           f32x4 v = acc[ni][mi];
;           if (nt >= LDP) continue;
;           if ((nt >= C_VS && nt < C_KW) || (nt >= C_VW && nt < C_GATE)) {
;             const bool isw = nt >= C_VW;
;             const int off = n - (isw ? C_VW : C_VS);
;             const int g = off >> 6, d = off & 63;
;             u16* dst = (isw ? p.vtw : p.vts) + ((size_t)(b * 2 + g) * 64 + d) * LDT + t;
; #pragma unroll
;             for (int r = 0; r < 4; ++r) dst[(size_t)r * LDT] = f2bf(v[r]);
;           } else {
;             const bool rope_tile = ((nt >= C_KS && nt < C_VS) || (nt >= C_KW && nt < C_VW)) && ((nt & 63) == 0);
;             if (rope_tile) {
; #pragma unroll
;               for (int r = 0; r < 4; ++r) {
;                 const float pr = __shfl_xor(v[r], 32);
;                 const int i = ((quad & 1) << 2) + r;
;                 const float cs = p.rope[(size_t)m * 16 + i], sn = p.rope[(size_t)m * 16 + 8 + i];
;                 v[r] = (quad < 2) ? (v[r] * cs - pr * sn) : (v[r] * cs + pr * sn);
;               }
;             }
;             uint2 pk; pk.x = pack2(v[0], v[1]); pk.y = pack2(v[2], v[3]);
;             *(uint2*)(p.proj + (size_t)m * LDP + n) = pk;
;           }
;         }
.LBB0_312:
	s_cmp_gt_i32 s47, 13
	s_cbranch_scc1 .Lp1_slow_epilogue
	s_load_dwordx2 s[76:77], s[68:69], 0xe8
	v_and_b32_e32 v180, 63, v210
	v_lshrrev_b32_e32 v181, 6, v210
	v_lshlrev_b32_e32 v182, 11, v181
	v_add_u32_e32 v182, 0x10000, v182
	v_lshl_add_u32 v182, v102, 7, v182
	v_and_b32_e32 v183, 1, v103
	v_lshl_add_u32 v182, v183, 3, v182
	v_lshrrev_b32_e32 v183, 1, v103
	v_and_b32_e32 v184, 7, v102
	v_xor_b32_e32 v183, v183, v184
	v_xor_b32_e32 v185, 0, v183
	v_lshl_add_u32 v186, v185, 4, v182
	v_xor_b32_e32 v185, 2, v183
	v_lshl_add_u32 v187, v185, 4, v182
	v_xor_b32_e32 v185, 4, v183
	v_lshl_add_u32 v188, v185, 4, v182
	v_xor_b32_e32 v185, 6, v183
	v_lshl_add_u32 v189, v185, 4, v182
	v_lshrrev_b32_e32 v184, 3, v180
	v_and_b32_e32 v185, 7, v180
	v_lshlrev_b32_e32 v190, 11, v181
	v_add_u32_e32 v190, 0x10000, v190
	v_lshl_add_u32 v190, v184, 7, v190
	v_lshl_add_u32 v190, v185, 4, v190
	v_xor_b32_e32 v185, v185, v184
	v_lshlrev_b32_e32 v185, 4, v185
	v_mul_u32_u24_e32 v191, 0x1240, v184
	v_add_u32_e32 v191, v191, v185
	v_lshl_add_u32 v192, v105, 6, s5
	v_mul_lo_u32 v192, v192, s43
	v_lshl_or_b32 v193, v104, 6, s4
	v_lshl_add_u32 v192, v193, 1, v192
	s_nop 0
	v_readfirstlane_b32 s78, v192
	s_waitcnt lgkmcnt(0)
	s_add_u32 s76, s76, s78
	s_addc_u32 s77, s77, 0
	v_cvt_pk_bf16_f32 v194, v60, v61
	v_cvt_pk_bf16_f32 v195, v62, v63
	ds_write_b64 v186, v[194:195]
	v_cvt_pk_bf16_f32 v196, v56, v57
	v_cvt_pk_bf16_f32 v197, v58, v59
	ds_write_b64 v187, v[196:197]
	v_cvt_pk_bf16_f32 v198, v52, v53
	v_cvt_pk_bf16_f32 v199, v54, v55
	ds_write_b64 v188, v[198:199]
	v_cvt_pk_bf16_f32 v200, v48, v49
	v_cvt_pk_bf16_f32 v201, v50, v51
	ds_write_b64 v189, v[200:201]
	s_waitcnt lgkmcnt(0)
	ds_read_b128 v[212:215], v190
	ds_read_b128 v[216:219], v190 offset:1024
	s_waitcnt lgkmcnt(1)
	global_store_dwordx4 v191, v[212:215], s[76:77]
	v_add_u32_e32 v191, 0x9200, v191
	s_waitcnt lgkmcnt(0)
	global_store_dwordx4 v191, v[216:219], s[76:77]
	v_add_u32_e32 v191, 0x9200, v191
	v_cvt_pk_bf16_f32 v194, v44, v45
	v_cvt_pk_bf16_f32 v195, v46, v47
	ds_write_b64 v186, v[194:195]
	v_cvt_pk_bf16_f32 v196, v40, v41
	v_cvt_pk_bf16_f32 v197, v42, v43
	ds_write_b64 v187, v[196:197]
	v_cvt_pk_bf16_f32 v198, v36, v37
	v_cvt_pk_bf16_f32 v199, v38, v39
	ds_write_b64 v188, v[198:199]
	v_cvt_pk_bf16_f32 v200, v32, v33
	v_cvt_pk_bf16_f32 v201, v34, v35
	ds_write_b64 v189, v[200:201]
	s_waitcnt lgkmcnt(0)
	ds_read_b128 v[220:223], v190
	ds_read_b128 v[224:227], v190 offset:1024
	s_waitcnt lgkmcnt(1)
	global_store_dwordx4 v191, v[220:223], s[76:77]
	v_add_u32_e32 v191, 0x9200, v191
	s_waitcnt lgkmcnt(0)
	global_store_dwordx4 v191, v[224:227], s[76:77]
	v_add_u32_e32 v191, 0x9200, v191
	v_cvt_pk_bf16_f32 v194, v28, v29
	v_cvt_pk_bf16_f32 v195, v30, v31
	ds_write_b64 v186, v[194:195]
	v_cvt_pk_bf16_f32 v196, v24, v25
	v_cvt_pk_bf16_f32 v197, v26, v27
	ds_write_b64 v187, v[196:197]
	v_cvt_pk_bf16_f32 v198, v20, v21
	v_cvt_pk_bf16_f32 v199, v22, v23
	ds_write_b64 v188, v[198:199]
	v_cvt_pk_bf16_f32 v200, v16, v17
	v_cvt_pk_bf16_f32 v201, v18, v19
	ds_write_b64 v189, v[200:201]
	s_waitcnt lgkmcnt(0)
	ds_read_b128 v[212:215], v190
	ds_read_b128 v[216:219], v190 offset:1024
	s_waitcnt lgkmcnt(1)
	global_store_dwordx4 v191, v[212:215], s[76:77]
	v_add_u32_e32 v191, 0x9200, v191
	s_waitcnt lgkmcnt(0)
	global_store_dwordx4 v191, v[216:219], s[76:77]
	v_add_u32_e32 v191, 0x9200, v191
	v_cvt_pk_bf16_f32 v194, v12, v13
	v_cvt_pk_bf16_f32 v195, v14, v15
	ds_write_b64 v186, v[194:195]
	v_cvt_pk_bf16_f32 v196, v8, v9
	v_cvt_pk_bf16_f32 v197, v10, v11
	ds_write_b64 v187, v[196:197]
	v_cvt_pk_bf16_f32 v198, v4, v5
	v_cvt_pk_bf16_f32 v199, v6, v7
	ds_write_b64 v188, v[198:199]
	v_cvt_pk_bf16_f32 v200, v0, v1
	v_cvt_pk_bf16_f32 v201, v2, v3
	ds_write_b64 v189, v[200:201]
	s_waitcnt lgkmcnt(0)
	ds_read_b128 v[220:223], v190
	ds_read_b128 v[224:227], v190 offset:1024
	s_waitcnt lgkmcnt(1)
	global_store_dwordx4 v191, v[220:223], s[76:77]
	v_add_u32_e32 v191, 0x9200, v191
	s_waitcnt lgkmcnt(0)
	global_store_dwordx4 v191, v[224:227], s[76:77]
	v_add_u32_e32 v191, 0x9200, v191
	s_branch .LBB0_249
